# P4 prologue: per-unit rstd table rows computed by both wave halves on alternate units (halves the serial load round trips)
# speedup vs baseline: 1.0039x; 1.0039x over previous
; __global__ void __launch_bounds__(NWAVES * 64, 2) fwd_megakernel(Args args) {
;     ...
;         { pg8::Unit u; for (int ui = 0; S.next(ui, u); ++ui) if (tid < 256) { const int r = u.pm * 256 + tid; RSTD1[r] = __builtin_amdgcn_rsqf(pg8::sum16(PS + (size_t)r * 16) * (1.0f / 1024.0f) + RMS_EPS); }
.LBB0_641:
	s_or_b64 exec, exec, s[0:1]
	s_add_u32 s12, s70, 0x10000
	s_addc_u32 s13, s71, 0
	s_waitcnt lgkmcnt(0)
	v_mov_b64_e32 v[2:3], 0xb00
	v_mov_b64_e32 v[4:5], 0xaff
	s_movk_i32 s2, 0x161
	v_mov_b32_e32 v6, 0x358637bd
	s_mov_b64 s[0:1], s[80:81]
	s_barrier
	s_mov_b32 s98, 0
	s_branch .LBB0_644
.LBB0_642:
	s_or_b64 exec, exec, s[8:9]
	s_add_u32 s0, s0, s67
	s_addc_u32 s1, s1, s52
	s_xor_b32 s98, s98, 1
	s_mov_b64 s[8:9], 0

; __global__ void __launch_bounds__(NWAVES * 64, 2) fwd_megakernel(Args args) {
;     ...
;         { pg8::Unit u; for (int ui = 0; S.next(ui, u); ++ui) if (tid < 256) { const int r = u.pm * 256 + tid; RSTD1[r] = __builtin_amdgcn_rsqf(pg8::sum16(PS + (size_t)r * 16) * (1.0f / 1024.0f) + RMS_EPS); }
.LBB0_647:
	s_mov_b64 s[8:9], exec
	s_cmp_eq_u32 s98, 0
	s_cbranch_scc1 .Lrstd_even
	s_andn2_b64 exec, exec, s[6:7]
	s_branch .Lrstd_go
.Lrstd_even:
	s_and_b64 exec, exec, s[6:7]
.Lrstd_go:
	s_cbranch_execz .LBB0_642
	v_and_b32_e32 v24, 0xff, v178
	v_lshl_or_b32 v24, s3, 8, v24
	v_ashrrev_i32_e32 v25, 31, v24
	v_lshlrev_b64 v[8:9], 6, v[24:25]
	v_lshl_add_u64 v[26:27], s[14:15], 0, v[8:9]
	global_load_dwordx4 v[8:11], v[26:27], off
	global_load_dwordx4 v[12:15], v[26:27], off offset:16
	global_load_dwordx4 v[16:19], v[26:27], off offset:32
	global_load_dwordx4 v[20:23], v[26:27], off offset:48
	s_waitcnt vmcnt(3)
	v_mov_b32_e32 v26, v9
	v_mov_b32_e32 v27, v10
	v_mov_b32_e32 v9, v11
	s_waitcnt vmcnt(2)
	v_mov_b32_e32 v10, v13
	v_mov_b32_e32 v11, v14
	v_mov_b32_e32 v13, v15
	v_pk_add_f32 v[8:9], v[26:27], v[8:9]
	v_pk_add_f32 v[10:11], v[10:11], v[12:13]
	v_pk_add_f32 v[8:9], v[8:9], v[8:9] op_sel:[0,1] op_sel_hi:[1,0]
	v_pk_add_f32 v[10:11], v[10:11], v[10:11] op_sel:[0,1] op_sel_hi:[1,0]
	s_waitcnt vmcnt(1)
	v_add_f32_e32 v14, v16, v17
	v_add_f32_e32 v16, v18, v19
	s_waitcnt vmcnt(0)
	v_mov_b32_e32 v15, v22
	v_mov_b32_e32 v17, v23
	v_mov_b32_e32 v9, v20
	v_mov_b32_e32 v11, v21
	v_pk_add_f32 v[8:9], v[8:9], v[10:11]
	v_pk_add_f32 v[10:11], v[14:15], v[16:17]
	s_nop 0
	v_pk_add_f32 v[8:9], v[8:9], v[10:11]
	s_nop 0
	v_add_f32_e32 v7, v8, v9
	v_fmamk_f32 v7, v7, 0x3a800000, v6
	v_rsq_f32_e32 v7, v7
	v_lshl_add_u64 v[8:9], v[24:25], 2, s[12:13]
	global_store_dword v[8:9], v7, off
	s_branch .LBB0_642
